# t11 with the P1-end store drain + barrier only on the 64 forget-logit producer workgroups (others publish without draining)
# speedup vs baseline: 1.0082x; 1.0082x over previous
.LBB0_317:
	s_cmp_gt_i32 s71, 2
	s_cselect_b64 s[0:1], -1, 0
	s_and_b64 s[2:3], s[34:35], s[0:1]
	s_andn2_b64 vcc, exec, s[2:3]
	s_cbranch_vccnz .LBB0_371
	s_cmpk_lg_i32 s92, 0x100
	s_cbranch_scc1 .Lsyn_drain
	s_and_b32 s4, s76, 0xc0
	s_cmp_lg_u32 s4, 0x40
	s_cbranch_scc1 .Lsyn_nodrain

.Lsyn_nodrain:
	v_cmp_eq_u32_e32 vcc, 0, v161
	s_and_saveexec_b64 s[2:3], vcc
	s_cbranch_execz .Lsyn_pub_done
	s_cmpk_lg_i32 s92, 0x100
	s_cbranch_scc1 .Lsyn_dowb
	s_and_b32 s4, s76, 0xc0
	s_cmp_lg_u32 s4, 0x40
	s_cbranch_scc1 .Lsyn_nowb
